# in1 transposed K/V copy: bank-conflict-free rotated LDS gathers with whole-line stores
# baseline (speedup 1.0000x reference)
; DI int tid512() { int t = threadIdx_x_raw(); asm volatile("" : "+v"(t)); return t; }
;   DI void operator()(bf16_t* sCb) const {
;     ...
;       if (nt >= 4 && nt < 12) {
;         bf16_t* tp = (bf16_t*)(ws + (nt < 8 ? OFF_RKT : OFF_RVT));
;         int hh = (nt - 4) & 3;
;         for (int id = tid512(); id < 128 * 32; id += 512) {
;           int col = id & 127, rch = id >> 7;
;           unsigned short e[8];
; #pragma unroll
;           for (int j = 0; j < 8; ++j) e[j] = base[(rch * 8 + j) * BLD + col];
;           u32x4 o = {(unsigned)e[0] | ((unsigned)e[1] << 16), (unsigned)e[2] | ((unsigned)e[3] << 16), (unsigned)e[4] | ((unsigned)e[5] << 16), (unsigned)e[6] | ((unsigned)e[7] << 16)};
;           *(u32x4*)(tp + ((size_t)(b * 4 + hh) * 128 + col) * 4096 + s0 + rch * 8) = o;
;         }
.LBB0_793:
	v_mov_b32_e32 v1, v196
	s_nop 0
	v_cmp_gt_i32_e32 vcc, s50, v1
	s_and_saveexec_b64 s[26:27], vcc
	s_cbranch_execz .LBB0_772
	s_and_b32 s28, s57, 3
	s_or_b32 s28, s28, s53
	s_ashr_i32 s29, s28, 31
	s_lshl_b64 s[28:29], s[28:29], 20
	s_add_u32 s28, s55, s28
	s_addc_u32 s29, s56, s29
	v_and_b32_e32 v2, 7, v196
	v_bfe_u32 v3, v196, 3, 5
	v_lshrrev_b32_e32 v4, 8, v196
	v_lshl_or_b32 v2, v4, 3, v2
	v_mul_u32_u24_e32 v0, 0x1080, v3
	v_lshl_add_u32 v0, v2, 1, v0
	v_add_u32_e32 v0, s58, v0
	v_lshlrev_b32_e32 v128, 13, v2
	v_lshl_add_u32 v128, v3, 4, v128
	v_lshl_add_u64 v[2:3], s[28:29], 0, v[128:129]
	s_mov_b32 s30, 0x20000
	s_mov_b32 s31, 0
	v_bfe_u32 v4, v196, 3, 2
	v_and_b32_e32 v5, 1, v4
	v_cmp_ne_u32_e64 s[60:61], 0, v5
	v_and_b32_e32 v5, 2, v4
	v_cmp_ne_u32_e64 s[62:63], 0, v5
	v_lshlrev_b32_e32 v4, 1, v4
	v_add_u32_e32 v5, 0, v4
	v_and_b32_e32 v5, 7, v5
	v_mul_u32_u24_e32 v5, 0x210, v5
	v_add_u32_e32 v34, v0, v5
	v_add_u32_e32 v5, 1, v4
	v_and_b32_e32 v5, 7, v5
	v_mul_u32_u24_e32 v5, 0x210, v5
	v_add_u32_e32 v35, v0, v5
	v_add_u32_e32 v5, 2, v4
	v_and_b32_e32 v5, 7, v5
	v_mul_u32_u24_e32 v5, 0x210, v5
	v_add_u32_e32 v36, v0, v5
	v_add_u32_e32 v5, 3, v4
	v_and_b32_e32 v5, 7, v5
	v_mul_u32_u24_e32 v5, 0x210, v5
	v_add_u32_e32 v37, v0, v5
	v_add_u32_e32 v5, 4, v4
	v_and_b32_e32 v5, 7, v5
	v_mul_u32_u24_e32 v5, 0x210, v5
	v_add_u32_e32 v38, v0, v5
	v_add_u32_e32 v5, 5, v4
	v_and_b32_e32 v5, 7, v5
	v_mul_u32_u24_e32 v5, 0x210, v5
	v_add_u32_e32 v39, v0, v5
	v_add_u32_e32 v5, 6, v4
	v_and_b32_e32 v5, 7, v5
	v_mul_u32_u24_e32 v5, 0x210, v5
	v_add_u32_e32 v40, v0, v5
	v_add_u32_e32 v5, 7, v4
	v_and_b32_e32 v5, 7, v5
	v_mul_u32_u24_e32 v5, 0x210, v5
	v_add_u32_e32 v41, v0, v5
	ds_read_u16 v10, v34
	ds_read_u16 v11, v35
	ds_read_u16 v12, v36
	ds_read_u16 v13, v37
	ds_read_u16 v14, v38
	ds_read_u16 v15, v39
	ds_read_u16 v16, v40
	ds_read_u16 v17, v41
	ds_read_u16 v18, v34 offset:32
	ds_read_u16 v19, v35 offset:32
	ds_read_u16 v20, v36 offset:32
	ds_read_u16 v21, v37 offset:32
	ds_read_u16 v22, v38 offset:32
	ds_read_u16 v23, v39 offset:32
	ds_read_u16 v24, v40 offset:32
	ds_read_u16 v25, v41 offset:32
	s_waitcnt lgkmcnt(8)
	v_perm_b32 v26, v11, v10, s51
	v_perm_b32 v27, v13, v12, s51
	v_perm_b32 v28, v15, v14, s51
	v_perm_b32 v29, v17, v16, s51
	v_cndmask_b32_e64 v30, v26, v29, s[60:61]
	v_cndmask_b32_e64 v31, v27, v26, s[60:61]
	v_cndmask_b32_e64 v32, v28, v27, s[60:61]
	v_cndmask_b32_e64 v33, v29, v28, s[60:61]
	v_cndmask_b32_e64 v4, v30, v32, s[62:63]
	v_cndmask_b32_e64 v5, v31, v33, s[62:63]
	v_cndmask_b32_e64 v6, v32, v30, s[62:63]
	v_cndmask_b32_e64 v7, v33, v31, s[62:63]
	global_store_dwordx4 v[2:3], v[4:7], off
	v_lshl_add_u64 v[2:3], v[2:3], 0, s[30:31]
	ds_read_u16 v10, v34 offset:64
	ds_read_u16 v11, v35 offset:64
	ds_read_u16 v12, v36 offset:64
	ds_read_u16 v13, v37 offset:64
	ds_read_u16 v14, v38 offset:64
	ds_read_u16 v15, v39 offset:64
	ds_read_u16 v16, v40 offset:64
	ds_read_u16 v17, v41 offset:64
	s_waitcnt lgkmcnt(8)
	v_perm_b32 v26, v19, v18, s51
	v_perm_b32 v27, v21, v20, s51
	v_perm_b32 v28, v23, v22, s51
	v_perm_b32 v29, v25, v24, s51
	v_cndmask_b32_e64 v30, v26, v29, s[60:61]
	v_cndmask_b32_e64 v31, v27, v26, s[60:61]
	v_cndmask_b32_e64 v32, v28, v27, s[60:61]
	v_cndmask_b32_e64 v33, v29, v28, s[60:61]
	v_cndmask_b32_e64 v4, v30, v32, s[62:63]
	v_cndmask_b32_e64 v5, v31, v33, s[62:63]
	v_cndmask_b32_e64 v6, v32, v30, s[62:63]
	v_cndmask_b32_e64 v7, v33, v31, s[62:63]
	global_store_dwordx4 v[2:3], v[4:7], off
	v_lshl_add_u64 v[2:3], v[2:3], 0, s[30:31]
	ds_read_u16 v18, v34 offset:96
	ds_read_u16 v19, v35 offset:96
	ds_read_u16 v20, v36 offset:96
	ds_read_u16 v21, v37 offset:96
	ds_read_u16 v22, v38 offset:96
	ds_read_u16 v23, v39 offset:96
	ds_read_u16 v24, v40 offset:96
	ds_read_u16 v25, v41 offset:96
	s_waitcnt lgkmcnt(8)
; DI int tid512() { int t = threadIdx_x_raw(); asm volatile("" : "+v"(t)); return t; }
;   DI void operator()(bf16_t* sCb) const {
;     ...
;       if (nt >= 4 && nt < 12) {
;         bf16_t* tp = (bf16_t*)(ws + (nt < 8 ? OFF_RKT : OFF_RVT));
;         int hh = (nt - 4) & 3;
;         for (int id = tid512(); id < 128 * 32; id += 512) {
;           int col = id & 127, rch = id >> 7;
;           unsigned short e[8];
; #pragma unroll
;           for (int j = 0; j < 8; ++j) e[j] = base[(rch * 8 + j) * BLD + col];
;           u32x4 o = {(unsigned)e[0] | ((unsigned)e[1] << 16), (unsigned)e[2] | ((unsigned)e[3] << 16), (unsigned)e[4] | ((unsigned)e[5] << 16), (unsigned)e[6] | ((unsigned)e[7] << 16)};
;           *(u32x4*)(tp + ((size_t)(b * 4 + hh) * 128 + col) * 4096 + s0 + rch * 8) = o;
;         }
	v_perm_b32 v26, v11, v10, s51
	v_perm_b32 v27, v13, v12, s51
	v_perm_b32 v28, v15, v14, s51
	v_perm_b32 v29, v17, v16, s51
	v_cndmask_b32_e64 v30, v26, v29, s[60:61]
	v_cndmask_b32_e64 v31, v27, v26, s[60:61]
	v_cndmask_b32_e64 v32, v28, v27, s[60:61]
	v_cndmask_b32_e64 v33, v29, v28, s[60:61]
	v_cndmask_b32_e64 v4, v30, v32, s[62:63]
	v_cndmask_b32_e64 v5, v31, v33, s[62:63]
	v_cndmask_b32_e64 v6, v32, v30, s[62:63]
	v_cndmask_b32_e64 v7, v33, v31, s[62:63]
	global_store_dwordx4 v[2:3], v[4:7], off
	v_lshl_add_u64 v[2:3], v[2:3], 0, s[30:31]
	ds_read_u16 v10, v34 offset:128
	ds_read_u16 v11, v35 offset:128
	ds_read_u16 v12, v36 offset:128
	ds_read_u16 v13, v37 offset:128
	ds_read_u16 v14, v38 offset:128
	ds_read_u16 v15, v39 offset:128
	ds_read_u16 v16, v40 offset:128
	ds_read_u16 v17, v41 offset:128
	s_waitcnt lgkmcnt(8)
	v_perm_b32 v26, v19, v18, s51
	v_perm_b32 v27, v21, v20, s51
	v_perm_b32 v28, v23, v22, s51
	v_perm_b32 v29, v25, v24, s51
	v_cndmask_b32_e64 v30, v26, v29, s[60:61]
	v_cndmask_b32_e64 v31, v27, v26, s[60:61]
	v_cndmask_b32_e64 v32, v28, v27, s[60:61]
	v_cndmask_b32_e64 v33, v29, v28, s[60:61]
	v_cndmask_b32_e64 v4, v30, v32, s[62:63]
	v_cndmask_b32_e64 v5, v31, v33, s[62:63]
	v_cndmask_b32_e64 v6, v32, v30, s[62:63]
	v_cndmask_b32_e64 v7, v33, v31, s[62:63]
	global_store_dwordx4 v[2:3], v[4:7], off
	v_lshl_add_u64 v[2:3], v[2:3], 0, s[30:31]
	ds_read_u16 v18, v34 offset:160
	ds_read_u16 v19, v35 offset:160
	ds_read_u16 v20, v36 offset:160
	ds_read_u16 v21, v37 offset:160
	ds_read_u16 v22, v38 offset:160
	ds_read_u16 v23, v39 offset:160
	ds_read_u16 v24, v40 offset:160
	ds_read_u16 v25, v41 offset:160
	s_waitcnt lgkmcnt(8)
	v_perm_b32 v26, v11, v10, s51
	v_perm_b32 v27, v13, v12, s51
	v_perm_b32 v28, v15, v14, s51
	v_perm_b32 v29, v17, v16, s51
	v_cndmask_b32_e64 v30, v26, v29, s[60:61]
	v_cndmask_b32_e64 v31, v27, v26, s[60:61]
	v_cndmask_b32_e64 v32, v28, v27, s[60:61]
	v_cndmask_b32_e64 v33, v29, v28, s[60:61]
	v_cndmask_b32_e64 v4, v30, v32, s[62:63]
	v_cndmask_b32_e64 v5, v31, v33, s[62:63]
	v_cndmask_b32_e64 v6, v32, v30, s[62:63]
	v_cndmask_b32_e64 v7, v33, v31, s[62:63]
	global_store_dwordx4 v[2:3], v[4:7], off
	v_lshl_add_u64 v[2:3], v[2:3], 0, s[30:31]
	ds_read_u16 v10, v34 offset:192
	ds_read_u16 v11, v35 offset:192
	ds_read_u16 v12, v36 offset:192
	ds_read_u16 v13, v37 offset:192
	ds_read_u16 v14, v38 offset:192
	ds_read_u16 v15, v39 offset:192
	ds_read_u16 v16, v40 offset:192
	ds_read_u16 v17, v41 offset:192
	s_waitcnt lgkmcnt(8)
	v_perm_b32 v26, v19, v18, s51
	v_perm_b32 v27, v21, v20, s51
	v_perm_b32 v28, v23, v22, s51
	v_perm_b32 v29, v25, v24, s51
	v_cndmask_b32_e64 v30, v26, v29, s[60:61]
	v_cndmask_b32_e64 v31, v27, v26, s[60:61]
	v_cndmask_b32_e64 v32, v28, v27, s[60:61]
	v_cndmask_b32_e64 v33, v29, v28, s[60:61]
	v_cndmask_b32_e64 v4, v30, v32, s[62:63]
	v_cndmask_b32_e64 v5, v31, v33, s[62:63]
	v_cndmask_b32_e64 v6, v32, v30, s[62:63]
	v_cndmask_b32_e64 v7, v33, v31, s[62:63]
	global_store_dwordx4 v[2:3], v[4:7], off
	v_lshl_add_u64 v[2:3], v[2:3], 0, s[30:31]
	ds_read_u16 v18, v34 offset:224
	ds_read_u16 v19, v35 offset:224
	ds_read_u16 v20, v36 offset:224
	ds_read_u16 v21, v37 offset:224
	ds_read_u16 v22, v38 offset:224
	ds_read_u16 v23, v39 offset:224
	ds_read_u16 v24, v40 offset:224
	ds_read_u16 v25, v41 offset:224
	s_waitcnt lgkmcnt(8)
	v_perm_b32 v26, v11, v10, s51
	v_perm_b32 v27, v13, v12, s51
	v_perm_b32 v28, v15, v14, s51
	v_perm_b32 v29, v17, v16, s51
	v_cndmask_b32_e64 v30, v26, v29, s[60:61]
	v_cndmask_b32_e64 v31, v27, v26, s[60:61]
	v_cndmask_b32_e64 v32, v28, v27, s[60:61]
	v_cndmask_b32_e64 v33, v29, v28, s[60:61]
	v_cndmask_b32_e64 v4, v30, v32, s[62:63]
	v_cndmask_b32_e64 v5, v31, v33, s[62:63]
	v_cndmask_b32_e64 v6, v32, v30, s[62:63]
	v_cndmask_b32_e64 v7, v33, v31, s[62:63]
	global_store_dwordx4 v[2:3], v[4:7], off
	v_lshl_add_u64 v[2:3], v[2:3], 0, s[30:31]
	s_waitcnt lgkmcnt(0)
	v_perm_b32 v26, v19, v18, s51
	v_perm_b32 v27, v21, v20, s51
	v_perm_b32 v28, v23, v22, s51
	v_perm_b32 v29, v25, v24, s51
	v_cndmask_b32_e64 v30, v26, v29, s[60:61]
	v_cndmask_b32_e64 v31, v27, v26, s[60:61]
	v_cndmask_b32_e64 v32, v28, v27, s[60:61]
	v_cndmask_b32_e64 v33, v29, v28, s[60:61]
	v_cndmask_b32_e64 v4, v30, v32, s[62:63]
	v_cndmask_b32_e64 v5, v31, v33, s[62:63]
	v_cndmask_b32_e64 v6, v32, v30, s[62:63]
	v_cndmask_b32_e64 v7, v33, v31, s[62:63]
	global_store_dwordx4 v[2:3], v[4:7], off
	s_branch .LBB0_772
